# att21 = att14 + placement (9.3): unreachable s_nop pads behind each edited region so every downstream hot loop sits at the baseline's byte phase mod 64 (att14 had P4-P8 shifted by 4 mod 8)
# baseline (speedup 1.0000x reference)
.LBB0_298:
	v_lshlrev_b32_e32 v0, 1, v234
	v_and_b32_e32 v241, 32, v0
	v_lshlrev_b32_e32 v0, 4, v234
	v_and_b32_e32 v0, 0xc0, v0
	v_lshl_or_b32 v239, v252, 8, v0
	v_add_u32_e32 v0, 0, v241
	v_add3_u32 v248, v0, v238, v239
	v_max3_f32 v0, v18, v19, v2
	v_max3_f32 v36, v20, v21, v3
	s_and_b32 s1, s51, 0x3fffffc0
	v_max3_f32 v0, v0, v4, v5
	v_max3_f32 v36, v36, v24, v25
	s_lshl_b32 s1, s1, 2
	v_max3_f32 v0, v0, v22, v23
	v_max3_f32 v36, v36, v8, v9
	s_add_i32 s45, s1, 0
	v_max3_f32 v0, v0, v6, v7
	v_max3_f32 v36, v36, v28, v29
	s_add_i32 s45, s45, 0x12000
	v_max3_f32 v0, v0, v26, v27
	v_max3_f32 v36, v36, v12, v13
	s_cmp_lg_u32 0, -1
	v_max3_f32 v0, v0, v10, v11
	v_max3_f32 v36, v36, v32, v33
	s_mov_b32 s6, 1
	v_max3_f32 v0, v0, v30, v31
	v_max3_f32 v36, v36, v16, v17
	s_mov_b32 s19, 0
	v_max3_f32 v0, v0, v14, v15
	v_lshlrev_b32_e32 v249, 4, v252
	v_max_f32_e32 v0, v0, v36
	v_lshl_add_u32 v240, v236, 2, s45
	v_mov_b32_e32 v36, v0
	s_nop 1
	v_permlane32_swap_b32_e32 v0, v36
	v_max_f32_e32 v0, v0, v36
	s_nop 0
	v_add_f32_e32 v243, v1, v0
	v_sub_f32_e32 v2, v2, v0
	v_sub_f32_e32 v3, v3, v0
	v_sub_f32_e32 v18, v18, v0
	v_sub_f32_e32 v19, v19, v0
	v_sub_f32_e32 v20, v20, v0
	s_nop 0
	v_xor_b32_e32 v80, 0x80000000, v243
	v_mov_b32_e32 v81, v80
	v_mov_b32_e32 v82, v80
	v_mov_b32_e32 v83, v80
	v_mov_b32_e32 v84, v80
	v_mov_b32_e32 v85, v80
	v_mov_b32_e32 v86, v80
	v_mov_b32_e32 v87, v80
	v_mov_b32_e32 v88, v80
	v_mov_b32_e32 v89, v80
	v_mov_b32_e32 v90, v80
	v_mov_b32_e32 v91, v80
	v_mov_b32_e32 v92, v80
	v_mov_b32_e32 v93, v80
	v_mov_b32_e32 v94, v80
	v_mov_b32_e32 v95, v80
	s_waitcnt vmcnt(0) lgkmcnt(0)
	s_barrier
	v_exp_f32_e32 v96, v2
	v_exp_f32_e32 v97, v3
	v_lshl_add_u64 v[2:3], v[224:225], 0, s[12:13]
	s_mov_b32 s1, m0
	s_mov_b32 m0, s46
	s_nop 0
	global_load_lds_dwordx4 v[2:3], off
	s_mov_b32 m0, s1
	s_cselect_b32 s1, 0, 0
	s_add_i32 s2, s1, s0
	v_lshl_add_u64 v[2:3], v[34:35], 0, s[8:9]
	s_add_i32 s0, s2, 0xa000
	s_mov_b32 s1, m0
	s_mov_b32 m0, s0
	s_nop 0
	global_load_lds_dwordx4 v[2:3], off
	s_mov_b32 m0, s1
	s_mov_b64 s[0:1], 0x20080
	v_lshl_add_u64 v[2:3], v[34:35], 0, s[0:1]
	s_add_i32 s2, s2, 0xc000
	s_mov_b32 s0, m0
	s_mov_b32 m0, s2
	s_nop 0
	global_load_lds_dwordx4 v[2:3], off
	s_mov_b32 m0, s0
	ds_read_b128 v[220:223], v247 offset:8192
	ds_read_b128 v[216:219], v247 offset:8704
	ds_read_b128 v[212:215], v247 offset:10240
	ds_read_b128 v[208:211], v247 offset:10752
	ds_read_b128 v[204:207], v247 offset:12288
	ds_read_b128 v[200:203], v247 offset:12800
	ds_read_b128 v[196:199], v247 offset:14336
	ds_read_b128 v[192:195], v247 offset:14848
	v_sub_f32_e32 v4, v4, v0
	v_sub_f32_e32 v21, v21, v0
	v_sub_f32_e32 v5, v5, v0
	v_sub_f32_e32 v22, v22, v0
	v_sub_f32_e32 v6, v6, v0
	v_sub_f32_e32 v23, v23, v0
	v_sub_f32_e32 v7, v7, v0
	v_sub_f32_e32 v24, v24, v0
	v_sub_f32_e32 v8, v8, v0
	v_sub_f32_e32 v25, v25, v0
	v_sub_f32_e32 v9, v9, v0
	v_sub_f32_e32 v26, v26, v0
	v_sub_f32_e32 v10, v10, v0
	v_sub_f32_e32 v27, v27, v0
	v_sub_f32_e32 v11, v11, v0
	v_sub_f32_e32 v28, v28, v0
	v_sub_f32_e32 v12, v12, v0
	v_sub_f32_e32 v29, v29, v0
	v_sub_f32_e32 v13, v13, v0
	v_sub_f32_e32 v30, v30, v0
	v_sub_f32_e32 v14, v14, v0
	v_sub_f32_e32 v31, v31, v0
	v_sub_f32_e32 v15, v15, v0
	v_sub_f32_e32 v32, v32, v0
	v_sub_f32_e32 v16, v16, v0
	v_sub_f32_e32 v33, v33, v0
	v_sub_f32_e32 v0, v17, v0
	v_exp_f32_e32 v112, v18
	v_exp_f32_e32 v113, v19
	v_exp_f32_e32 v114, v20
	v_exp_f32_e32 v115, v21
	v_exp_f32_e32 v116, v22
	v_exp_f32_e32 v117, v23
	v_exp_f32_e32 v118, v24
	v_exp_f32_e32 v119, v25
	v_exp_f32_e32 v120, v26
	v_exp_f32_e32 v121, v27
	v_exp_f32_e32 v122, v28
	v_exp_f32_e32 v123, v29
	v_exp_f32_e32 v124, v30
	v_exp_f32_e32 v125, v31
	v_exp_f32_e32 v126, v32
	v_exp_f32_e32 v127, v33
	v_exp_f32_e32 v98, v4
	v_exp_f32_e32 v99, v5
	v_exp_f32_e32 v100, v6
	v_exp_f32_e32 v101, v7
	v_exp_f32_e32 v102, v8
	v_exp_f32_e32 v103, v9
	v_exp_f32_e32 v104, v10
	v_exp_f32_e32 v105, v11
	v_exp_f32_e32 v106, v12
	v_exp_f32_e32 v107, v13
	v_exp_f32_e32 v108, v14
	v_exp_f32_e32 v109, v15
	v_exp_f32_e32 v110, v16
	v_exp_f32_e32 v111, v0
	s_waitcnt vmcnt(3) lgkmcnt(0)
	s_barrier
	v_and_b32_e32 v0, 3, v234
	s_andn2_b64 vcc, exec, s[56:57]
	v_cmp_gt_u32_e64 s[2:3], 32, v235
	v_lshlrev_b32_e32 v226, 4, v0
	s_cbranch_vccnz .LBB0_314
	s_lshl_b32 s0, s51, 9
	v_mov_b32_e32 v227, v1
	s_and_b32 s0, s0, 0x18000
	v_lshl_add_u64 v[2:3], s[76:77], 1, v[226:227]
	v_lshl_or_b32 v0, v251, 11, s0
	v_lshl_add_u64 v[2:3], v[2:3], 0, v[0:1]
	v_mov_b32_e32 v14, v1
	v_mov_b32_e32 v15, v1
	v_lshl_add_u64 v[228:229], s[66:67], 0, v[2:3]
	v_readfirstlane_b32 s98, v224
	v_readfirstlane_b32 s99, v225
	s_nop 0
	v_readfirstlane_b32 s100, v228
	v_readfirstlane_b32 s101, v229
	s_nop 1
	v_subrev_u32_e32 v253, s98, v224
	v_subrev_u32_e32 v255, s100, v228
	s_add_u32 s98, s98, 0x80000
	s_addc_u32 s99, s99, 0
	s_add_u32 s100, s100, 0x13040000
	s_addc_u32 s101, s101, 0
	v_mov_b32_e32 v0, v1
	v_mov_b32_e32 v2, v1
	v_mov_b32_e32 v3, v1
	v_mov_b32_e32 v4, v1
	v_mov_b32_e32 v5, v1
	v_mov_b32_e32 v6, v1
	v_mov_b32_e32 v7, v1
	v_mov_b32_e32 v8, v1
	v_mov_b32_e32 v9, v1
	v_mov_b32_e32 v10, v1
	v_mov_b32_e32 v11, v1
	v_mov_b32_e32 v12, v1
	v_mov_b32_e32 v13, v1
	v_mov_b64_e32 v[30:31], v[14:15]
	v_mov_b64_e32 v[46:47], v[14:15]
	v_mov_b64_e32 v[62:63], v[14:15]
	v_mov_b64_e32 v[78:79], v[14:15]
	s_mov_b32 s0, 0
	s_movk_i32 s19, 0x4000
	s_movk_i32 s38, 0x2000
	v_mov_b32_e32 v250, 0
	s_mov_b64 s[72:73], 0
	v_mov_b64_e32 v[28:29], v[12:13]
	v_mov_b64_e32 v[26:27], v[10:11]
	v_mov_b64_e32 v[24:25], v[8:9]
	v_mov_b64_e32 v[22:23], v[6:7]
	v_mov_b64_e32 v[20:21], v[4:5]
	v_mov_b64_e32 v[18:19], v[2:3]
	v_mov_b64_e32 v[16:17], v[0:1]
	v_mov_b64_e32 v[44:45], v[12:13]
	v_mov_b64_e32 v[42:43], v[10:11]
	v_mov_b64_e32 v[40:41], v[8:9]
	v_mov_b64_e32 v[38:39], v[6:7]
	v_mov_b64_e32 v[36:37], v[4:5]
	v_mov_b64_e32 v[34:35], v[2:3]
	v_mov_b64_e32 v[32:33], v[0:1]
	v_mov_b64_e32 v[60:61], v[12:13]
	v_mov_b64_e32 v[58:59], v[10:11]
	v_mov_b64_e32 v[56:57], v[8:9]
	v_mov_b64_e32 v[54:55], v[6:7]
	v_mov_b64_e32 v[52:53], v[4:5]
	v_mov_b64_e32 v[50:51], v[2:3]
	v_mov_b64_e32 v[48:49], v[0:1]
	v_mov_b64_e32 v[76:77], v[12:13]
	v_mov_b64_e32 v[74:75], v[10:11]
	v_mov_b64_e32 v[72:73], v[8:9]
	v_mov_b64_e32 v[70:71], v[6:7]
	v_mov_b64_e32 v[68:69], v[4:5]
	v_mov_b64_e32 v[66:67], v[2:3]
	v_mov_b64_e32 v[64:65], v[0:1]
	s_nop 0
	s_nop 0

.LBB0_311:
	v_max_f32_e32 v2, v2, v2
	v_max_f32_e32 v2, 0, v2
	v_exp_f32_e64 v3, -v2
	v_add_f32_e32 v243, v243, v2
	v_xor_b32_e32 v80, 0x80000000, v243
	v_mov_b32_e32 v81, v80
	v_mov_b32_e32 v82, v80
	v_mov_b32_e32 v83, v80
	v_mov_b32_e32 v84, v80
	v_mov_b32_e32 v85, v80
	v_mov_b32_e32 v86, v80
	v_mov_b32_e32 v87, v80
	v_mov_b32_e32 v88, v80
	v_mov_b32_e32 v89, v80
	v_mov_b32_e32 v90, v80
	v_mov_b32_e32 v91, v80
	v_mov_b32_e32 v92, v80
	v_mov_b32_e32 v93, v80
	v_mov_b32_e32 v94, v80
	v_mov_b32_e32 v95, v80
	s_and_saveexec_b64 s[0:1], s[2:3]
	ds_write_b32 v240, v3
	s_or_b64 exec, exec, s[0:1]
	v_sub_f32_e32 v127, v127, v2
	v_sub_f32_e32 v126, v126, v2
	v_sub_f32_e32 v125, v125, v2
	v_sub_f32_e32 v124, v124, v2
	v_sub_f32_e32 v123, v123, v2
	v_sub_f32_e32 v122, v122, v2
	v_sub_f32_e32 v121, v121, v2
	v_sub_f32_e32 v120, v120, v2
	v_sub_f32_e32 v119, v119, v2
	v_sub_f32_e32 v118, v118, v2
	v_sub_f32_e32 v117, v117, v2
	v_sub_f32_e32 v116, v116, v2
	v_sub_f32_e32 v115, v115, v2
	v_sub_f32_e32 v114, v114, v2
	v_sub_f32_e32 v113, v113, v2
	v_sub_f32_e32 v112, v112, v2
	v_sub_f32_e32 v111, v111, v2
	v_sub_f32_e32 v110, v110, v2
	v_sub_f32_e32 v109, v109, v2
	v_sub_f32_e32 v108, v108, v2
	v_sub_f32_e32 v107, v107, v2
	v_sub_f32_e32 v106, v106, v2
	v_sub_f32_e32 v105, v105, v2
	v_sub_f32_e32 v104, v104, v2
	v_sub_f32_e32 v103, v103, v2
	v_sub_f32_e32 v102, v102, v2
	v_sub_f32_e32 v101, v101, v2
	v_sub_f32_e32 v100, v100, v2
	v_sub_f32_e32 v99, v99, v2
	v_sub_f32_e32 v98, v98, v2
	v_sub_f32_e32 v97, v97, v2
	v_sub_f32_e32 v96, v96, v2
	v_mul_f32_e32 v250, v250, v3
	s_branch .LBB0_304
	s_nop 0
	s_nop 0
	s_nop 0
	s_nop 0

.Lci_x29:
	v_mov_b32_e32 v111, v252
	s_branch .LBB0_461
	s_nop 0
	s_nop 0
	s_nop 0
	s_nop 0
	s_nop 0

.LBB0_712:
	s_or_b64 exec, exec, s[0:1]
	s_andn2_b64 vcc, exec, s[8:9]
	s_mov_b64 s[0:1], -1
	s_cbranch_vccnz .LBB0_697
	s_andn2_b64 vcc, exec, s[14:15]
	s_cbranch_vccnz .LBB0_696
	s_barrier
	s_branch .LBB0_696
	s_nop 0
	s_nop 0
	s_nop 0
	s_nop 0
	s_nop 0
	s_nop 0
	s_nop 0
	s_nop 0
	s_nop 0
	s_nop 0
	s_nop 0
	s_nop 0
	s_nop 0
	s_nop 0
